# attention unit prologues: q/gate load waits moved behind the barrier, LDS zeroing and first DMA issue (unitA) or dropped in favour of the band loop's own wait (unitB)
# speedup vs baseline: 1.0030x; 1.0030x over previous
; __device__ __forceinline__ unsigned src_off(int w, int lane, int ldB) { const int R = 8 * w + (lane >> 3), cch = (lane & 7) ^ swz(R); return (unsigned)(R * ldB + cch * 16); }
; __device__ __forceinline__ void unitB(unsigned char* lds, PG8_LAS unsigned char* lds3, const Args& a, int b, int kvh, int T) {
;     ...
;     int tq[2]; bf16x8 q[2][2]; unsigned long long sw[2][2];
; #pragma unroll
;     for (int cg_ = 0; cg_ < 2; ++cg_) {
;         tq[cg_] = t0 + 8 * w + 4 * cg_ + (c >> 2);
;         const bf16_t* rowp = a.PQ + (size_t)(b * SEQ + tq[cg_]) * PQ_LD;
; #pragma unroll
;         for (int dc = 0; dc < 2; ++dc) q[cg_][dc] = *(const bf16x8*)(rowp + 1304 + hb * 64 + 32 * dc + 8 * fq);
;         sw[cg_][0] = 0ull; sw[cg_][1] = 0ull;
;     }
; #pragma unroll
;     for (int cg_ = 0; cg_ < 2; ++cg_)
; #pragma unroll
;         for (int dc = 0; dc < 2; ++dc) asm volatile("" : "+v"(q[cg_][dc]));
;     const float farb = btab[128 * 16 + H];
;     const unsigned soff = src_off(w, lane, 128);
;     float m[2] = {-1e30f, -1e30f}, l[2] = {0.f, 0.f}; f32x4 o[2][4];
; #pragma unroll
;     for (int cg_ = 0; cg_ < 2; ++cg_)
; #pragma unroll
;         for (int df = 0; df < 4; ++df) o[cg_][df] = (f32x4){0.f, 0.f, 0.f, 0.f};
;     band_loop<false>(lds, lds3, (const unsigned char*)a.KVB + (size_t)bg * 128 * SLOTB, T, T - 2 > 0 ? T - 2 : 0, T, 128, q, tq, sw, H, farb, m, l, o, wu, soff, r, fq);
.LBB0_2137:
	s_lshl_b32 s28, s0, 6
	s_mov_b64 s[10:11], -1
	s_and_b64 vcc, exec, s[8:9]
	s_cbranch_vccz .LBB0_2223
	v_mov_b32_e32 v22, v198
	s_lshr_b32 s1, s36, 1
	v_ashrrev_i32_e32 v20, 6, v22
	v_lshlrev_b32_e32 v19, 3, v20
	v_add_u32_e32 v0, s28, v19
	v_bfe_u32 v21, v22, 2, 2
	v_or_b32_e32 v0, v0, v21
	s_and_b32 s10, s36, 1
	v_and_b32_e32 v18, 3, v22
	v_lshl_add_u32 v116, s1, 13, v0
	v_lshl_or_b32 v132, s10, 2, v18
	v_mov_b64_e32 v[2:3], s[70:71]
	v_add_u32_e32 v114, 4, v116
	v_mad_i64_i32 v[4:5], s[6:7], v116, s60, v[2:3]
	v_lshlrev_b32_e32 v0, 7, v132
	v_mad_i64_i32 v[2:3], s[6:7], v114, s60, v[2:3]
	v_lshl_add_u64 v[4:5], v[4:5], 0, v[0:1]
	v_and_b32_e32 v6, 48, v22
	v_mov_b32_e32 v7, v1
	v_lshl_add_u64 v[2:3], v[2:3], 0, v[0:1]
	v_lshl_add_u64 v[8:9], v[4:5], 0, v[6:7]
	v_lshl_add_u64 v[14:15], v[2:3], 0, v[6:7]
	global_load_dwordx4 v[2:5], v[8:9], off offset:2608
	s_nop 0
	global_load_dwordx4 v[6:9], v[8:9], off offset:2672
	s_nop 0
	global_load_dwordx4 v[10:13], v[14:15], off offset:2608
	s_nop 0
	global_load_dwordx4 v[14:17], v[14:15], off offset:2672
	s_lshl_b32 s1, s1, 22
	s_lshl_b32 s4, s10, 21
	s_or_b32 s1, s4, s1
	v_lshl_add_u32 v26, v132, 2, s61
	v_readfirstlane_b32 s4, v20
	s_add_u32 s11, s75, s1
	v_bfe_u32 v0, v22, 3, 3
	v_lshlrev_b32_e32 v25, 2, v20
	s_addc_u32 s12, s76, 0
	s_lshl_b32 s29, s4, 10
	v_and_b32_e32 v23, 7, v22
	v_and_b32_e32 v24, 2, v0
	v_and_b32_e32 v25, 4, v25
	v_or_b32_e32 v0, v0, v19
	s_cmp_gt_i32 s0, -1
	v_bitop3_b32 v23, v25, v23, v24 bitop3:0x36
	v_lshlrev_b32_e32 v0, 7, v0
	s_cselect_b64 s[8:9], -1, 0
	v_lshl_or_b32 v0, v23, 4, v0
	s_and_b64 vcc, exec, s[8:9]
	ds_read_b32 v117, v26 offset:8224
	s_waitcnt lgkmcnt(0)
	s_barrier
	s_cbranch_vccz .LBB0_2224
	s_mov_b32 s1, s5
	s_lshl_b64 s[6:7], s[0:1], 14
	s_add_u32 s6, s11, s6
	s_addc_u32 s7, s12, s7
	v_lshl_add_u64 v[24:25], s[6:7], 0, v[0:1]
	s_add_i32 s1, s29, 0
	s_mov_b32 s4, m0
	s_mov_b32 m0, s1
	s_nop 0
	global_load_lds_dwordx4 v[24:25], off
	s_mov_b32 m0, s4
	v_lshl_add_u64 v[26:27], v[24:25], 0, s[62:63]
	s_addk_i32 s1, 0x2000
	s_mov_b32 s4, m0
	s_mov_b32 m0, s1
	s_nop 0
	global_load_lds_dwordx4 v[26:27], off
	s_mov_b32 m0, s4
	s_cmp_lt_i32 s0, 1
	s_cbranch_scc0 .LBB0_2225

; __device__ __forceinline__ float bf2f(unsigned short v) { return __uint_as_float(((unsigned)v) << 16); }
; __device__ __forceinline__ unsigned src_off(int w, int lane, int ldB) { const int R = 8 * w + (lane >> 3), cch = (lane & 7) ^ swz(R); return (unsigned)(R * ldB + cch * 16); }
; __device__ __forceinline__ void unitA(unsigned char* lds, PG8_LAS unsigned char* lds3, const Args& a, int b, int g, int T) {
;     ...
;     int tq[2]; bf16x8 q[2][2];
;     f32x4* stash = (f32x4*)(lds + OFF_STASH);
; #pragma unroll
;     for (int cg_ = 0; cg_ < 2; ++cg_) {
;         tq[cg_] = t0 + 8 * w + 4 * cg_ + (c >> 2);
;         const bf16_t* rowp = a.PQ + (size_t)(b * SEQ + tq[cg_]) * PQ_LD;
; #pragma unroll
;         for (int dc = 0; dc < 2; ++dc) q[cg_][dc] = *(const bf16x8*)(rowp + H * 64 + 32 * dc + 8 * fq);
;     }
; #pragma unroll
;     for (int cg_ = 0; cg_ < 2; ++cg_)
; #pragma unroll
;         for (int dc = 0; dc < 2; ++dc) asm volatile("" : "+v"(q[cg_][dc]));
;     float gatev[3][2];
; #pragma unroll
;     for (int cg_ = 0; cg_ < 2; ++cg_)
; #pragma unroll
;         for (int br = 0; br < 3; ++br) { gatev[br][cg_] = bf2f(a.PQ[(size_t)(b * SEQ + tq[cg_]) * PQ_LD + 1280 + br * 8 + H]); asm volatile("" : "+v"(gatev[br][cg_])); }
;     ...
;     const float farb = btab[128 * 16 + H];
;     const unsigned soff = src_off(w, lane, 128);
;     __syncthreads();
;     for (int i = tid; i < 64 * IMP_LD; i += 512) imp[i] = 0.f;
.LBB0_2228:
	v_mov_b32_e32 v133, v198
	s_lshl_b32 s1, s36, 2
	v_ashrrev_i32_e32 v141, 6, v133
	v_and_b32_e32 v134, 3, v133
	v_lshlrev_b32_e32 v132, 3, v141
	v_and_or_b32 v19, s1, 4, v134
	v_add_u32_e32 v0, s28, v132
	v_bfe_u32 v135, v133, 2, 2
	s_lshl_b32 s1, s36, 12
	v_or_b32_e32 v4, v0, v135
	s_and_b32 s1, s1, 0x7fffe000
	v_lshlrev_b32_e32 v0, 7, v19
	v_lshl_add_u64 v[2:3], s[70:71], 0, v[0:1]
	v_and_b32_e32 v0, 48, v133
	v_add_u32_e32 v152, s1, v4
	v_lshl_add_u64 v[2:3], v[2:3], 0, v[0:1]
	v_add_u32_e32 v150, 4, v152
	v_mad_i64_i32 v[6:7], s[8:9], v152, s60, v[2:3]
	v_mad_i64_i32 v[14:15], s[8:9], v150, s60, v[2:3]
	global_load_dwordx4 v[2:5], v[6:7], off
	s_nop 0
	global_load_dwordx4 v[6:9], v[6:7], off offset:64
	s_nop 0
	global_load_dwordx4 v[10:13], v[14:15], off
	s_nop 0
	global_load_dwordx4 v[14:17], v[14:15], off offset:64
	v_mov_b64_e32 v[20:21], s[70:71]
	v_lshlrev_b32_e32 v0, 1, v19
	v_mad_i64_i32 v[22:23], s[8:9], v152, s60, v[20:21]
	v_lshl_add_u64 v[22:23], v[22:23], 0, v[0:1]
	v_mad_i64_i32 v[20:21], s[8:9], v150, s60, v[20:21]
	v_lshl_add_u64 v[20:21], v[20:21], 0, v[0:1]
	v_lshl_add_u32 v177, v19, 2, s61
	s_movk_i32 s1, 0x2040
	v_readfirstlane_b32 s4, v141
	v_cmp_gt_i32_e32 vcc, s1, v133
	global_load_ushort v144, v[22:23], off offset:2560
	global_load_ushort v139, v[22:23], off offset:2576
	global_load_ushort v174, v[22:23], off offset:2592
	global_load_ushort v143, v[20:21], off offset:2560
	global_load_ushort v138, v[20:21], off offset:2576
	global_load_ushort v173, v[20:21], off offset:2592
	ds_read_b32 v18, v177 offset:8192
	s_waitcnt lgkmcnt(0)
	s_barrier
	s_and_saveexec_b64 s[8:9], vcc
	s_cbranch_execz .LBB0_2231
	v_add_u32_e32 v0, 0xfffffe00, v133
	v_lshl_add_u32 v20, v133, 2, s65
	s_mov_b64 s[10:11], 0

; __device__ __forceinline__ float bf2f(unsigned short v) { return __uint_as_float(((unsigned)v) << 16); }
; __device__ __forceinline__ unsigned src_off(int w, int lane, int ldB) { const int R = 8 * w + (lane >> 3), cch = (lane & 7) ^ swz(R); return (unsigned)(R * ldB + cch * 16); }
; __device__ __forceinline__ void unitA(unsigned char* lds, PG8_LAS unsigned char* lds3, const Args& a, int b, int g, int T) {
;     ...
;     float gatev[3][2];
; #pragma unroll
;     for (int cg_ = 0; cg_ < 2; ++cg_)
; #pragma unroll
;         for (int br = 0; br < 3; ++br) { gatev[br][cg_] = bf2f(a.PQ[(size_t)(b * SEQ + tq[cg_]) * PQ_LD + 1280 + br * 8 + H]); asm volatile("" : "+v"(gatev[br][cg_])); }
;     ...
;     const float farb = btab[128 * 16 + H];
;     const unsigned soff = src_off(w, lane, 128);
;     __syncthreads();
;     for (int i = tid; i < 64 * IMP_LD; i += 512) imp[i] = 0.f;
;     f32x4 oc[2][4];
;     for (int rep_ = 0; rep_ < REP_CMP; ++rep_) {
;         const int NB = ((4 * T + 2) >> 6) + 1;
;         const int ib_far = (64 * T - 1167) >= 0 ? (64 * T - 1167) / 1024 : -1;
;         const unsigned char* Kb = (const unsigned char*)(a.KC + (size_t)bg * 512 * 64); const unsigned char* Vb = (const unsigned char*)(a.VCT + (size_t)bg * 64 * 512);
;         const unsigned voffc = src_off(w, lane, 1024);
;         float m[2] = {-1e30f, -1e30f}, l[2] = {0.f, 0.f}, moff[2];
;         __syncthreads();
; #pragma unroll
;         for (int pi = 0; pi < 3; ++pi) if (pi < NB) dma_block(lds3, pi, wu, Kb + (size_t)pi * 8192, soff, Vb + pi * 128, voffc);
.LBB0_2237:
	s_waitcnt vmcnt(0)
	v_lshlrev_b32_e32 v144, 16, v144
	v_lshlrev_b32_e32 v139, 16, v139
	v_lshlrev_b32_e32 v174, 16, v174
	v_lshlrev_b32_e32 v143, 16, v143
	v_lshlrev_b32_e32 v138, 16, v138
	v_lshlrev_b32_e32 v173, 16, v173
	v_lshlrev_b32_e32 v19, 1, v20
	s_add_i32 s4, s28, 0xfffffb71
	v_and_b32_e32 v20, 6, v133
	v_and_or_b32 v19, v19, 24, v134
	s_lshr_b32 s4, s4, 10
	v_bitop3_b32 v20, v142, v20, 4 bitop3:0x36
	v_lshlrev_b32_e32 v19, 7, v19
	v_bitop3_b32 v21, v142, v133, 6 bitop3:0x78
	v_lshlrev_b32_e32 v137, 4, v20
	v_lshlrev_b32_e32 v20, 7, v142
	s_cmp_gt_i32 s0, 18
	v_add_u32_e32 v140, 0, v19
	v_add3_u32 v19, v135, s28, v132
	v_lshlrev_b32_e32 v136, 4, v21
	s_cselect_b32 s18, s4, -1
	s_and_b64 vcc, exec, s[8:9]
	v_sub_u32_e32 v98, v19, v20
	v_lshl_add_u64 v[110:111], v[86:87], 0, s[2:3]
	s_cbranch_vccz .LBB0_2322
	v_mov_b32_e32 v19, v18
	v_mov_b32_e32 v20, v18
	v_mov_b32_e32 v21, v18
	v_add_u32_e32 v99, 0xfffffd71, v98
	v_lshl_add_u64 v[96:97], v[86:87], 0, s[2:3]
	v_mov_b32_e32 v103, 0xf149f2ca
	v_mov_b32_e32 v102, 0
	s_mov_b32 s19, 0
	s_movk_i32 s4, 0x180
	s_mov_b32 s20, s1
	v_mov_b32_e32 v100, 0
	v_mov_b32_e32 v101, 0xf149f2ca
	s_mov_b32 s21, 0
	s_cmp_lt_i32 s20, 2
	s_mov_b64 s[14:15], -1
	s_cbranch_scc0 .LBB0_2245
	s_branch .LBB0_2240
